# strategy 6: LDS bank-conflict XOR swizzle of the phase A operand tiles (DMA source chunk and fragment read address)
# baseline (speedup 1.0000x reference)
; DI int my_tid() { int t = threadIdx.x; asm volatile("" : "+v"(t)); return t; }
;     ...
;   const int tid = my_tid(), lane = tid & 63, w = __builtin_amdgcn_readfirstlane(tid >> 6), wa = w >> 2, wb = w & 3, qi = lane & 15, quad = lane >> 4;
;   const bf16_t* base = w >= 4 ? Bg : Ag; const int ld = (int)(w >= 4 ? ldb : lda);
;   const bf16_t* nbase = nAg ? (w >= 4 ? nBg : nAg) : base;
;   unsigned off[8];
; #pragma unroll
;   for (int u = 0; u < 8; ++u) {
;     const int blk = (w & 3) * 8 + u, rg = blk >> 1, kh = blk & 1;
;     int R = rg * 16 + (lane >> 2);
;     if (perm) { const int rho = R & 31; R = (R & ~31) + ((rho >> 2) & 3) * 8 + (rho >> 4) * 4 + (rho & 3); }
;     off[u] = (unsigned)(R * ld + kh * 32 + (lane & 3) * 8);
;   }
;   const int ra = (wa * 8) * 2 * 1024 + (qi * 4 + quad) * 16, rb = (wb * 4) * 2 * 1024 + (qi * 4 + quad) * 16;
;     ...
;     const bf16_t* Xg = p.xb() + (long)mtl * 256 * LDX; const bf16_t* Wg = Wt + (long)ntl * 256 * LDX;
;     f32x4 acc[8][4]; zero_acc(acc);
;     const int kstep = (fake == 1 || fake == 2) ? 0 : 64;
;     int mt2, nt2;
;     const bool more = !fake && tile_order(sl, it + 1, NT_IN, mt2, nt2);
;     const bf16_t* Xn = more ? p.xb() + (long)mt2 * 256 * LDX : Xg; const bf16_t* Wn = more ? Wt + (long)nt2 * 256 * LDX : Wg;
;     const bool vn = more ? nt2 >= 21 : nt >= 21;
;     gemm_core(nt >= 21 ? Xg : Wg, LDX, nt >= 21 ? Wg : Xg, LDX, D_MODEL, gl, acc, kstep, !fake && it > 0, vn ? Xn : Wn, vn ? Wn : Xn, true);
.LBB0_262:
	s_or_b64 exec, exec, s[8:9]
	v_mov_b64_e32 v[2:3], s[18:19]
	s_mov_b32 s12, 0x88000
	v_mad_i64_i32 v[8:9], s[8:9], v162, s12, v[2:3]
	v_mov_b64_e32 v[2:3], v[8:9]
	s_and_saveexec_b64 s[8:9], vcc
	v_mov_b64_e32 v[2:3], s[18:19]
	v_mad_i64_i32 v[2:3], s[10:11], v204, s12, v[2:3]
	s_or_b64 exec, exec, s[8:9]
	v_mov_b64_e32 v[4:5], s[14:15]
	v_mad_i64_i32 v[10:11], s[8:9], v202, s12, v[4:5]
	s_mov_b32 s13, 0x88000
	v_mov_b32_e32 v13, v202
	v_mov_b64_e32 v[4:5], v[10:11]
	s_and_saveexec_b64 s[8:9], vcc
	v_mov_b64_e32 v[4:5], s[14:15]
	v_mad_i64_i32 v[4:5], s[10:11], v203, s13, v[4:5]
	v_mov_b32_e32 v13, v203
	s_or_b64 exec, exec, s[8:9]
	v_mov_b32_e32 v12, v210
	v_cmp_gt_i32_e64 s[8:9], 21, v202
	v_lshlrev_b32_e32 v6, 3, v12
	v_readfirstlane_b32 s30, v12
	v_and_b32_e32 v7, 24, v6
	v_lshrrev_b32_e32 v15, 4, v12
	v_sub_u32_e32 v15, 0, v15
	v_and_b32_e32 v15, 3, v15
	v_lshlrev_b32_e32 v15, 3, v15
	v_xor_b32_e32 v7, v7, v15
	v_lshrrev_b32_e32 v6, 1, v12
	s_ashr_i32 s10, s30, 6
	v_lshrrev_b32_e32 v0, 2, v12
	v_and_b32_e32 v6, 24, v6
	s_and_b32 s29, s10, 3
	v_and_or_b32 v0, v0, 3, v6
	v_lshl_or_b32 v14, s29, 6, v0
	s_cmp_gt_i32 s10, 3
	v_mul_u32_u24_e32 v15, 0x440, v14
	v_cmp_lt_i32_e32 vcc, 20, v202
	s_cselect_b64 s[12:13], -1, 0
	s_cmp_eq_u32 s27, 0
	v_add_u32_e32 v6, v15, v7
	s_cbranch_scc1 .LBB0_270
	v_add_u32_e32 v0, v15, v7
	s_mov_b64 s[40:41], 0
	v_mov_b32_e32 v143, v0
	v_mov_b64_e32 v[132:133], v[0:1]
	s_branch .LBB0_271

;     ...
;   const bf16_t* base = w >= 4 ? Bg : Ag; const int ld = (int)(w >= 4 ? ldb : lda);
;   const bf16_t* nbase = nAg ? (w >= 4 ? nBg : nAg) : base;
;   unsigned off[8];
; #pragma unroll
;   for (int u = 0; u < 8; ++u) {
;     const int blk = (w & 3) * 8 + u, rg = blk >> 1, kh = blk & 1;
;     int R = rg * 16 + (lane >> 2);
;     if (perm) { const int rho = R & 31; R = (R & ~31) + ((rho >> 2) & 3) * 8 + (rho >> 4) * 4 + (rho & 3); }
;     off[u] = (unsigned)(R * ld + kh * 32 + (lane & 3) * 8);
;   }
;   const int ra = (wa * 8) * 2 * 1024 + (qi * 4 + quad) * 16, rb = (wb * 4) * 2 * 1024 + (qi * 4 + quad) * 16;
;   unsigned char* buf0 = lds; unsigned char* buf1 = lds + STAGE_B;
;   const int KT = K >> 6;
;   if (!pre) {
;     g_dma(base, off, 0, buf0, w);
;     asm volatile("s_waitcnt vmcnt(0)" ::: "memory");
;     __syncthreads();
;   }
;   for (int kt = 0; kt < KT; kt += 2) {
;     g_dma(base, off, (kt + 1) * kstep, buf1, w);
;     ...
;     f32x4 acc[8][4]; zero_acc(acc);
;     const int kstep = (fake == 1 || fake == 2) ? 0 : 64;
;     int mt2, nt2;
;     const bool more = !fake && tile_order(sl, it + 1, NT_IN, mt2, nt2);
;     const bf16_t* Xn = more ? p.xb() + (long)mt2 * 256 * LDX : Xg; const bf16_t* Wn = more ? Wt + (long)nt2 * 256 * LDX : Wg;
;     const bool vn = more ? nt2 >= 21 : nt >= 21;
;     gemm_core(nt >= 21 ? Xg : Wg, LDX, nt >= 21 ? Wg : Xg, LDX, D_MODEL, gl, acc, kstep, !fake && it > 0, vn ? Xn : Wn, vn ? Wn : Xn, true);
.LBB0_273:
	v_cmp_lt_i32_e32 vcc, 20, v13
	s_nop 1
	v_cndmask_b32_e32 v7, v5, v3, vcc
	v_cndmask_b32_e32 v6, v4, v2, vcc
	v_cndmask_b32_e32 v0, v2, v4, vcc
	v_cndmask_b32_e32 v2, v3, v5, vcc
	v_and_b32_e32 v3, 48, v12
	v_cndmask_b32_e64 v135, v7, v2, s[12:13]
	v_cndmask_b32_e64 v134, v6, v0, s[12:13]
	s_lshl_b32 s12, s30, 6
	v_lshlrev_b32_e32 v0, 6, v12
	s_movk_i32 s13, 0x3c0
	s_and_b32 s12, s12, 0xffffc000
	v_and_or_b32 v0, v0, s13, v3
	v_lshrrev_b32_e32 v4, 2, v12
	v_sub_u32_e32 v4, 0, v4
	v_and_b32_e32 v4, 3, v4
	v_lshlrev_b32_e32 v4, 4, v4
	v_xor_b32_e32 v0, v0, v4
	v_mov_b32_e32 v2, 0
	v_cmp_eq_u64_e64 s[10:11], 0, v[6:7]
	v_or_b32_e32 v144, s12, v0
	v_lshl_or_b32 v145, s29, 13, v0
	s_mov_b32 s29, 0
	s_mov_b32 s12, 0
	v_mov_b32_e32 v3, v2
	v_mov_b32_e32 v4, v2
	v_mov_b32_e32 v5, v2
	v_mov_b32_e32 v6, v2
	v_mov_b32_e32 v7, v2
	v_mov_b32_e32 v8, v2
	v_mov_b32_e32 v9, v2
	v_mov_b32_e32 v18, v2
	v_mov_b32_e32 v19, v2
	v_mov_b32_e32 v20, v2
	v_mov_b32_e32 v21, v2
	v_mov_b32_e32 v26, v2
	v_mov_b32_e32 v27, v2
	v_mov_b32_e32 v28, v2
	v_mov_b32_e32 v29, v2
	v_mov_b32_e32 v10, v2
	v_mov_b32_e32 v11, v2
	v_mov_b32_e32 v12, v2
	v_mov_b32_e32 v13, v2
	v_mov_b32_e32 v14, v2
	v_mov_b32_e32 v15, v2
	v_mov_b32_e32 v16, v2
	v_mov_b32_e32 v17, v2
	v_mov_b32_e32 v22, v2
	v_mov_b32_e32 v23, v2
	v_mov_b32_e32 v24, v2
	v_mov_b32_e32 v25, v2
	v_mov_b32_e32 v30, v2
	v_mov_b32_e32 v31, v2
	v_mov_b32_e32 v32, v2
	v_mov_b32_e32 v33, v2
	v_mov_b32_e32 v34, v2
	v_mov_b32_e32 v35, v2
	v_mov_b32_e32 v36, v2
	v_mov_b32_e32 v37, v2
	v_mov_b32_e32 v42, v2
	v_mov_b32_e32 v43, v2
	v_mov_b32_e32 v44, v2
	v_mov_b32_e32 v45, v2
	v_mov_b32_e32 v50, v2
	v_mov_b32_e32 v51, v2
	v_mov_b32_e32 v52, v2
	v_mov_b32_e32 v53, v2
	v_mov_b32_e32 v58, v2
	v_mov_b32_e32 v59, v2
	v_mov_b32_e32 v60, v2
	v_mov_b32_e32 v61, v2
	v_mov_b32_e32 v38, v2
	v_mov_b32_e32 v39, v2
	v_mov_b32_e32 v40, v2
	v_mov_b32_e32 v41, v2
	v_mov_b32_e32 v46, v2
	v_mov_b32_e32 v47, v2
	v_mov_b32_e32 v48, v2
	v_mov_b32_e32 v49, v2
	v_mov_b32_e32 v54, v2
	v_mov_b32_e32 v55, v2
	v_mov_b32_e32 v56, v2
	v_mov_b32_e32 v57, v2
	v_mov_b32_e32 v62, v2
	v_mov_b32_e32 v63, v2
	v_mov_b32_e32 v64, v2
	v_mov_b32_e32 v65, v2
	v_mov_b32_e32 v66, v2
	v_mov_b32_e32 v67, v2
	v_mov_b32_e32 v68, v2
	v_mov_b32_e32 v69, v2
	v_mov_b32_e32 v74, v2
	v_mov_b32_e32 v75, v2
	v_mov_b32_e32 v76, v2
	v_mov_b32_e32 v77, v2
	v_mov_b32_e32 v82, v2
	v_mov_b32_e32 v83, v2
	v_mov_b32_e32 v84, v2
	v_mov_b32_e32 v85, v2
	v_mov_b32_e32 v90, v2
	v_mov_b32_e32 v91, v2
	v_mov_b32_e32 v92, v2
	v_mov_b32_e32 v93, v2
	v_mov_b32_e32 v70, v2
	v_mov_b32_e32 v71, v2
	v_mov_b32_e32 v72, v2
	v_mov_b32_e32 v73, v2
	v_mov_b32_e32 v78, v2
	v_mov_b32_e32 v79, v2
	v_mov_b32_e32 v80, v2
	v_mov_b32_e32 v81, v2
	v_mov_b32_e32 v86, v2
	v_mov_b32_e32 v87, v2
	v_mov_b32_e32 v88, v2
	v_mov_b32_e32 v89, v2
	v_mov_b32_e32 v94, v2
	v_mov_b32_e32 v95, v2
	v_mov_b32_e32 v96, v2
	v_mov_b32_e32 v97, v2
	v_mov_b32_e32 v98, v2
	v_mov_b32_e32 v99, v2
	v_mov_b32_e32 v100, v2
	v_mov_b32_e32 v101, v2
	v_mov_b32_e32 v106, v2
	v_mov_b32_e32 v107, v2
	v_mov_b32_e32 v108, v2
	v_mov_b32_e32 v109, v2
	v_mov_b32_e32 v114, v2
	v_mov_b32_e32 v115, v2
	v_mov_b32_e32 v116, v2
	v_mov_b32_e32 v117, v2
	v_mov_b32_e32 v122, v2
	v_mov_b32_e32 v123, v2
	v_mov_b32_e32 v124, v2
	v_mov_b32_e32 v125, v2
	v_mov_b32_e32 v102, v2
	v_mov_b32_e32 v103, v2
	v_mov_b32_e32 v104, v2
	v_mov_b32_e32 v105, v2
	v_mov_b32_e32 v110, v2
	v_mov_b32_e32 v111, v2
	v_mov_b32_e32 v112, v2
	v_mov_b32_e32 v113, v2
	v_mov_b32_e32 v118, v2
	v_mov_b32_e32 v119, v2
	v_mov_b32_e32 v120, v2
	v_mov_b32_e32 v121, v2
	v_mov_b32_e32 v126, v2
	v_mov_b32_e32 v127, v2
	v_mov_b32_e32 v128, v2
	v_mov_b32_e32 v129, v2
	v_lshlrev_b32_e32 v244, 1, v143
	v_add_u32_e32 v196, 32, v144
	v_add_u32_e32 v197, 0x10020, v144
	v_add_u32_e32 v198, 0x8020, v145
	v_add_u32_e32 v199, 0x18020, v145
	v_readfirstlane_b32 s40, v130
	v_readfirstlane_b32 s41, v131
	v_readfirstlane_b32 s42, v134
	v_readfirstlane_b32 s43, v135
	v_add_u32_e32 v245, 0x40, v244
	v_add_u32_e32 v246, 0x2200, v244
	v_add_u32_e32 v247, 0x2240, v244
	v_add_u32_e32 v248, 0x11000, v244
	v_add_u32_e32 v249, 0x11040, v244
	v_add_u32_e32 v250, 0x13200, v244
	v_add_u32_e32 v251, 0x13240, v244
	s_add_i32 s44, s28, 32
	s_add_i32 s45, s28, s35
	s_cmp_lg_u64 s[10:11], 0
	s_cselect_b64 s[42:43], s[40:41], s[42:43]
	s_add_u32 s40, s40, 0x80
	s_addc_u32 s41, s41, 0
	s_mov_b32 s47, 0
	s_cmp_eq_u32 s27, 0
	s_cbranch_scc1 .LgA_k1issue
	s_mov_b32 s47, s87
	s_branch .LgA_k1done
